# phase 0: s5_params coefficient pairs loaded up front (8 dwordx4), norm_rows<3> row copy batched and gain hoisted
# speedup vs baseline: 1.0839x; 1.0096x over previous
.LBB0_57:
	s_or_b64 exec, exec, s[2:3]
	s_waitcnt vmcnt(0)
	v_mul_f32_e32 v16, v10, v16
	s_mov_b32 s2, 0x3fb8aa3b
	v_mul_f32_e32 v21, 0x3fb8aa3b, v16
	v_fma_f32 v24, v16, s2, -v21
	v_rndne_f32_e32 v25, v21
	v_fmamk_f32 v24, v16, 0x32a5705f, v24
	v_sub_f32_e32 v21, v21, v25
	v_add_f32_e32 v21, v21, v24
	v_exp_f32_e32 v21, v21
	v_cvt_i32_f32_e32 v24, v25
	s_mov_b32 s2, 0xc2ce8ed0
	v_cmp_ngt_f32_e32 vcc, s2, v16
	s_mov_b32 s2, 0x42b17218
	v_ldexp_f32 v21, v21, v24
	v_cndmask_b32_e32 v21, 0, v21, vcc
	v_mov_b32_e32 v24, 0x7f800000
	v_cmp_nlt_f32_e32 vcc, s2, v16
	v_mul_f32_e32 v16, v20, v20
	v_mov_b32_e32 v27, 0xbab64f3b
	v_cndmask_b32_e32 v26, v24, v21, vcc
	v_mov_b32_e32 v24, 0x3c0881c4
	v_fmamk_f32 v21, v16, 0xb94c1982, v24
	v_fmaak_f32 v21, v16, v21, 0xbe2aaa9d
	v_mul_f32_e32 v21, v16, v21
	v_fmac_f32_e32 v20, v20, v21
	v_fmamk_f32 v21, v16, 0x37d75334, v27
	v_fmaak_f32 v21, v16, v21, 0x3d2aabf7
	v_fmaak_f32 v21, v16, v21, 0xbf000004
	v_fma_f32 v16, v16, v21, 1.0
	v_and_b32_e32 v21, 1, v17
	v_cmp_eq_u32_e32 vcc, 0, v21
	v_mul_hi_i32_i24_e32 v21, 0x48000, v19
	v_mov_b32_e32 v25, 0xbe2aaa9d
	v_cndmask_b32_e64 v16, -v20, v16, vcc
	v_mul_i32_i24_e32 v20, 0x48000, v19
	v_mul_f32_e32 v19, v23, v23
	v_fmac_f32_e32 v24, 0xb94c1982, v19
	v_mov_b32_e32 v28, 0x3d2aabf7
	v_fmac_f32_e32 v25, v19, v24
	v_fmac_f32_e32 v27, 0x37d75334, v19
	v_mov_b32_e32 v29, 0xbf000004
	v_lshlrev_b32_e32 v17, 30, v17
	s_brev_b32 s2, 1
	v_mul_f32_e32 v24, v19, v25
	v_fmac_f32_e32 v28, v19, v27
	v_bitop3_b32 v16, v17, v16, s2 bitop3:0x6c
	s_movk_i32 s2, 0x1f8
	v_fmac_f32_e32 v23, v23, v24
	v_fmac_f32_e32 v29, v19, v28
	v_and_b32_e32 v24, 1, v22
	v_lshlrev_b32_e32 v22, 30, v22
	v_cmp_class_f32_e64 vcc, v14, s2
	v_fma_f32 v19, v19, v29, 1.0
	v_cmp_eq_u32_e64 s[4:5], 0, v24
	v_and_b32_e32 v22, 0x80000000, v22
	v_xor_b32_e32 v14, v15, v14
	v_cndmask_b32_e64 v19, v19, v23, s[4:5]
	v_xor_b32_e32 v14, v14, v22
	v_mov_b32_e32 v17, 0x7fc00000
	v_xor_b32_e32 v14, v14, v19
	v_cndmask_b32_e32 v14, v17, v14, vcc
	v_cndmask_b32_e32 v30, v17, v16, vcc
	v_mul_f32_e32 v17, v26, v14
	v_lshlrev_b32_e32 v14, 3, v18
	v_lshl_add_u64 v[20:21], v[42:43], 0, v[20:21]
	s_mov_b64 s[2:3], 0x1ec32000
	v_and_b32_e32 v27, 0x1f8, v14
	v_lshl_add_u64 v[20:21], v[20:21], 0, s[2:3]
	v_lshl_or_b32 v14, v1, 9, v27
	v_mov_b32_e32 v15, 0
	v_mul_f32_e32 v16, v26, v30
	v_lshl_add_u64 v[18:19], v[20:21], 0, v[14:15]
	v_mul_f32_e32 v14, v17, v17
	global_store_dwordx2 v[18:19], v[16:17], off
	v_fma_f32 v14, v16, v16, -v14
	v_add_f32_e32 v16, v16, v16
	v_mul_f32_e32 v16, v16, v17
	v_mul_f32_e32 v22, v16, v16
	v_fma_f32 v22, v14, v14, -v22
	v_add_f32_e32 v14, v14, v14
	v_mul_f32_e32 v14, v16, v14
	v_mul_f32_e32 v16, v14, v14
	v_fma_f32 v16, v22, v22, -v16
	v_add_f32_e32 v22, v22, v22
	v_mul_f32_e32 v14, v14, v22
	v_mul_f32_e32 v22, v14, v14
	v_fma_f32 v22, v16, v16, -v22
	v_add_f32_e32 v16, v16, v16
	v_mul_f32_e32 v14, v14, v16
	v_mul_f32_e32 v16, v14, v14
	v_fma_f32 v16, v22, v22, -v16
	v_add_f32_e32 v22, v22, v22
	v_mul_f32_e32 v14, v14, v22
	v_mul_f32_e32 v22, v14, v14
	s_movk_i32 s2, 0x4000
	v_fma_f32 v22, v16, v16, -v22
	v_add_f32_e32 v16, v16, v16
	v_add_co_u32_e32 v18, vcc, s2, v18
	v_mul_f32_e32 v23, v14, v16
	s_nop 0
	v_addc_co_u32_e32 v19, vcc, 0, v19, vcc
	v_lshlrev_b64 v[8:9], 6, v[8:9]
	global_store_dwordx2 v[18:19], v[22:23], off
	v_lshl_add_u64 v[12:13], v[12:13], 0, v[8:9]
	v_lshl_add_u64 v[8:9], v[44:45], 0, v[8:9]
	global_load_dwordx4 v[100:103], v[8:9], off
	global_load_dwordx4 v[104:107], v[8:9], off offset:16
	global_load_dwordx4 v[108:111], v[8:9], off offset:32
	global_load_dwordx4 v[112:115], v[8:9], off offset:48
	global_load_dwordx4 v[116:119], v[12:13], off
	global_load_dwordx4 v[120:123], v[12:13], off offset:16
	global_load_dwordx4 v[124:127], v[12:13], off offset:32
	global_load_dwordx4 v[128:131], v[12:13], off offset:48
	v_pk_mul_f32 v[24:25], v[10:11], v[10:11]
	v_fma_f32 v16, v26, v30, -1.0
	v_add_f32_e32 v14, v24, v25
	v_div_scale_f32 v19, s[2:3], v14, v14, 1.0
	v_rcp_f32_e32 v23, v19
	s_mov_b32 s2, 0x9000
	v_fma_f32 v24, -v19, v23, 1.0
	v_fmac_f32_e32 v23, v24, v23
	v_div_scale_f32 v24, vcc, 1.0, v14, 1.0
	v_mul_f32_e32 v25, v24, v23
	v_fma_f32 v26, -v19, v25, v24
	v_fmac_f32_e32 v25, v26, v23
	v_fma_f32 v19, -v19, v25, v24
	v_div_fmas_f32 v19, v19, v23, v25
	v_div_fixup_f32 v24, v19, v14, 1.0
	v_lshl_or_b32 v14, v1, 13, v27
	v_lshl_add_u64 v[14:15], v[20:21], 0, v[14:15]
	v_mov_b32_e32 v20, v11
	v_pk_mul_f32 v[20:21], v[20:21], v[16:17] op_sel:[0,1] op_sel_hi:[0,0]
	v_pk_fma_f32 v[26:27], v[10:11], v[16:17], v[20:21]
	v_pk_fma_f32 v[10:11], v[10:11], v[16:17], v[20:21] op_sel_hi:[0,1,1] neg_lo:[0,0,1] neg_hi:[0,0,1]
	v_mov_b32_e32 v27, v11
	v_pk_mul_f32 v[10:11], v[24:25], v[26:27] op_sel_hi:[0,1]
	s_waitcnt vmcnt(0)
	v_mov_b32_e32 v18, v100
	v_mov_b32_e32 v22, v116
	v_pk_mul_f32 v[16:17], v[18:19], v[10:11] op_sel:[0,1] op_sel_hi:[0,0]
	v_pk_fma_f32 v[18:19], v[22:23], v[10:11], v[16:17] neg_lo:[0,0,1] neg_hi:[0,0,1]
	v_pk_fma_f32 v[16:17], v[22:23], v[10:11], v[16:17] op_sel_hi:[0,1,1]
	v_add_co_u32_e32 v16, vcc, s2, v14
	v_mov_b32_e32 v19, v17
	s_nop 0
	v_addc_co_u32_e32 v17, vcc, 0, v15, vcc
	global_store_dwordx2 v[16:17], v[18:19], off offset:-4096
	v_mov_b32_e32 v18, v101
	s_nop 0
	v_mov_b32_e32 v20, v117
	s_mov_b32 s2, 0x8000
	v_add_co_u32_e32 v14, vcc, s2, v14
	v_pk_mul_f32 v[18:19], v[18:19], v[10:11] op_sel:[0,1] op_sel_hi:[0,0]
	v_pk_fma_f32 v[22:23], v[20:21], v[10:11], v[18:19] neg_lo:[0,0,1] neg_hi:[0,0,1]
	v_pk_fma_f32 v[18:19], v[20:21], v[10:11], v[18:19] op_sel_hi:[0,1,1]
	v_addc_co_u32_e32 v15, vcc, 0, v15, vcc
	v_mov_b32_e32 v23, v19
	global_store_dwordx2 v[14:15], v[22:23], off offset:512
	v_mov_b32_e32 v18, v102
	v_mov_b32_e32 v20, v118
	v_pk_mul_f32 v[18:19], v[10:11], v[18:19] op_sel:[1,0] op_sel_hi:[0,0]
	v_pk_fma_f32 v[22:23], v[10:11], v[20:21], v[18:19] neg_lo:[0,0,1] neg_hi:[0,0,1]
	v_pk_fma_f32 v[18:19], v[10:11], v[20:21], v[18:19] op_sel_hi:[1,0,1]
	s_nop 0
	v_mov_b32_e32 v23, v19
	global_store_dwordx2 v[14:15], v[22:23], off offset:1024
	v_mov_b32_e32 v18, v103
	v_mov_b32_e32 v20, v119
	v_pk_mul_f32 v[18:19], v[10:11], v[18:19] op_sel:[1,0] op_sel_hi:[0,0]
	v_pk_fma_f32 v[22:23], v[10:11], v[20:21], v[18:19] neg_lo:[0,0,1] neg_hi:[0,0,1]
	v_pk_fma_f32 v[18:19], v[10:11], v[20:21], v[18:19] op_sel_hi:[1,0,1]
	s_nop 0
	v_mov_b32_e32 v23, v19
	global_store_dwordx2 v[14:15], v[22:23], off offset:1536
	v_mov_b32_e32 v18, v104
	v_mov_b32_e32 v20, v120
	v_pk_mul_f32 v[18:19], v[10:11], v[18:19] op_sel:[1,0] op_sel_hi:[0,0]
	v_pk_fma_f32 v[22:23], v[10:11], v[20:21], v[18:19] neg_lo:[0,0,1] neg_hi:[0,0,1]
	v_pk_fma_f32 v[18:19], v[10:11], v[20:21], v[18:19] op_sel_hi:[1,0,1]
	s_nop 0
	v_mov_b32_e32 v23, v19
	global_store_dwordx2 v[14:15], v[22:23], off offset:2048
	v_mov_b32_e32 v18, v105
	v_mov_b32_e32 v20, v121
	v_pk_mul_f32 v[18:19], v[10:11], v[18:19] op_sel:[1,0] op_sel_hi:[0,0]
	v_pk_fma_f32 v[22:23], v[10:11], v[20:21], v[18:19] neg_lo:[0,0,1] neg_hi:[0,0,1]
	v_pk_fma_f32 v[18:19], v[10:11], v[20:21], v[18:19] op_sel_hi:[1,0,1]
	s_nop 0
	v_mov_b32_e32 v23, v19
	global_store_dwordx2 v[14:15], v[22:23], off offset:2560
	v_mov_b32_e32 v18, v106
	v_mov_b32_e32 v20, v122
	v_pk_mul_f32 v[18:19], v[10:11], v[18:19] op_sel:[1,0] op_sel_hi:[0,0]
	v_pk_fma_f32 v[22:23], v[10:11], v[20:21], v[18:19] neg_lo:[0,0,1] neg_hi:[0,0,1]
	v_pk_fma_f32 v[18:19], v[10:11], v[20:21], v[18:19] op_sel_hi:[1,0,1]
	s_nop 0
	v_mov_b32_e32 v23, v19
	global_store_dwordx2 v[14:15], v[22:23], off offset:3072
	v_mov_b32_e32 v18, v107
	v_mov_b32_e32 v20, v123
	v_pk_mul_f32 v[18:19], v[10:11], v[18:19] op_sel:[1,0] op_sel_hi:[0,0]
	v_pk_fma_f32 v[22:23], v[10:11], v[20:21], v[18:19] neg_lo:[0,0,1] neg_hi:[0,0,1]
	v_pk_fma_f32 v[18:19], v[10:11], v[20:21], v[18:19] op_sel_hi:[1,0,1]
	s_nop 0
	v_mov_b32_e32 v23, v19
	global_store_dwordx2 v[14:15], v[22:23], off offset:3584
	v_mov_b32_e32 v14, v108
	s_nop 0
	v_mov_b32_e32 v18, v124
	v_pk_mul_f32 v[14:15], v[10:11], v[14:15] op_sel:[1,0] op_sel_hi:[0,0]
	v_pk_fma_f32 v[20:21], v[10:11], v[18:19], v[14:15] neg_lo:[0,0,1] neg_hi:[0,0,1]
	v_pk_fma_f32 v[14:15], v[10:11], v[18:19], v[14:15] op_sel_hi:[1,0,1]
	s_nop 0
	v_mov_b32_e32 v21, v15
	global_store_dwordx2 v[16:17], v[20:21], off
	v_mov_b32_e32 v14, v109
	v_mov_b32_e32 v18, v125
	v_pk_mul_f32 v[14:15], v[10:11], v[14:15] op_sel:[1,0] op_sel_hi:[0,0]
	v_pk_fma_f32 v[20:21], v[10:11], v[18:19], v[14:15] neg_lo:[0,0,1] neg_hi:[0,0,1]
	v_pk_fma_f32 v[14:15], v[10:11], v[18:19], v[14:15] op_sel_hi:[1,0,1]
	s_nop 0
	v_mov_b32_e32 v21, v15
	global_store_dwordx2 v[16:17], v[20:21], off offset:512
	v_mov_b32_e32 v14, v110
	v_mov_b32_e32 v18, v126
	v_pk_mul_f32 v[14:15], v[10:11], v[14:15] op_sel:[1,0] op_sel_hi:[0,0]
	v_pk_fma_f32 v[20:21], v[10:11], v[18:19], v[14:15] neg_lo:[0,0,1] neg_hi:[0,0,1]
	v_pk_fma_f32 v[14:15], v[10:11], v[18:19], v[14:15] op_sel_hi:[1,0,1]
	s_nop 0
	v_mov_b32_e32 v21, v15
	global_store_dwordx2 v[16:17], v[20:21], off offset:1024
	v_mov_b32_e32 v14, v111
	v_mov_b32_e32 v18, v127
	v_pk_mul_f32 v[14:15], v[10:11], v[14:15] op_sel:[1,0] op_sel_hi:[0,0]
	v_pk_fma_f32 v[20:21], v[10:11], v[18:19], v[14:15] neg_lo:[0,0,1] neg_hi:[0,0,1]
	v_pk_fma_f32 v[14:15], v[10:11], v[18:19], v[14:15] op_sel_hi:[1,0,1]
	s_nop 0
	v_mov_b32_e32 v21, v15
	global_store_dwordx2 v[16:17], v[20:21], off offset:1536
	v_mov_b32_e32 v14, v112
	v_mov_b32_e32 v18, v128
	v_pk_mul_f32 v[14:15], v[10:11], v[14:15] op_sel:[1,0] op_sel_hi:[0,0]
	v_pk_fma_f32 v[20:21], v[10:11], v[18:19], v[14:15] neg_lo:[0,0,1] neg_hi:[0,0,1]
	v_pk_fma_f32 v[14:15], v[10:11], v[18:19], v[14:15] op_sel_hi:[1,0,1]
	s_nop 0
	v_mov_b32_e32 v21, v15
	global_store_dwordx2 v[16:17], v[20:21], off offset:2048
	v_mov_b32_e32 v14, v113
	v_mov_b32_e32 v18, v129
	v_pk_mul_f32 v[14:15], v[10:11], v[14:15] op_sel:[1,0] op_sel_hi:[0,0]
	v_pk_fma_f32 v[20:21], v[10:11], v[18:19], v[14:15] neg_lo:[0,0,1] neg_hi:[0,0,1]
	v_pk_fma_f32 v[14:15], v[10:11], v[18:19], v[14:15] op_sel_hi:[1,0,1]
	s_nop 0
	v_mov_b32_e32 v21, v15
	global_store_dwordx2 v[16:17], v[20:21], off offset:2560
	v_mov_b32_e32 v14, v114
	v_mov_b32_e32 v18, v130
	v_pk_mul_f32 v[14:15], v[10:11], v[14:15] op_sel:[1,0] op_sel_hi:[0,0]
	v_pk_fma_f32 v[20:21], v[10:11], v[18:19], v[14:15] neg_lo:[0,0,1] neg_hi:[0,0,1]
	v_pk_fma_f32 v[14:15], v[10:11], v[18:19], v[14:15] op_sel_hi:[1,0,1]
	s_nop 0
	v_mov_b32_e32 v21, v15
	global_store_dwordx2 v[16:17], v[20:21], off offset:3072
	v_mov_b32_e32 v14, v115
	v_mov_b32_e32 v18, v131
	v_pk_mul_f32 v[8:9], v[10:11], v[14:15] op_sel:[1,0] op_sel_hi:[0,0]
	v_pk_fma_f32 v[12:13], v[10:11], v[18:19], v[8:9] neg_lo:[0,0,1] neg_hi:[0,0,1]
	v_pk_fma_f32 v[8:9], v[10:11], v[18:19], v[8:9] op_sel_hi:[1,0,1]
	s_nop 0
	v_mov_b32_e32 v13, v9
	global_store_dwordx2 v[16:17], v[12:13], off offset:3584
.LBB0_58:
	s_or_b64 exec, exec, s[0:1]
	v_mov_b32_e32 v1, v160
	v_readlane_b32 s0, v253, 0
	v_ashrrev_i32_e32 v8, 6, v1
	s_mov_b32 s12, 0x8100
	v_lshl_add_u32 v48, s0, 3, v8
	v_cmp_gt_i32_e32 vcc, s12, v48
	s_and_saveexec_b64 s[0:1], vcc
	s_cbranch_execz .LBB0_93
	v_mbcnt_lo_u32_b32 v8, -1, 0
	v_lshlrev_b32_e32 v1, 2, v1
	v_mbcnt_hi_u32_b32 v8, -1, v8
	v_and_b32_e32 v40, 0xfc, v1
	v_and_b32_e32 v1, 64, v8
	v_add_u32_e32 v9, 64, v1
	v_xor_b32_e32 v1, 1, v8
	v_cmp_lt_i32_e32 vcc, v1, v9
	v_xor_b32_e32 v10, 2, v8
	s_load_dword s2, s[40:41], 0x108
	v_cndmask_b32_e32 v1, v8, v1, vcc
	v_cmp_lt_i32_e32 vcc, v10, v9
	v_mov_b32_e32 v39, 0
	v_lshlrev_b32_e32 v38, 2, v40
	v_cndmask_b32_e32 v10, v8, v10, vcc
	v_lshlrev_b32_e32 v41, 2, v10
	v_xor_b32_e32 v10, 4, v8
	v_cmp_lt_i32_e32 vcc, v10, v9
	v_lshl_add_u64 v[44:45], v[6:7], 0, v[38:39]
	v_lshl_add_u64 v[46:47], v[42:43], 0, v[38:39]
	v_cndmask_b32_e32 v10, v8, v10, vcc
	v_lshlrev_b32_e32 v56, 2, v10
	v_xor_b32_e32 v10, 8, v8
	v_cmp_lt_i32_e32 vcc, v10, v9
	v_lshlrev_b32_e32 v38, 1, v40
	s_waitcnt lgkmcnt(0)
	s_lshl_b32 s13, s2, 3
	v_cndmask_b32_e32 v10, v8, v10, vcc
	v_lshlrev_b32_e32 v57, 2, v10
	v_xor_b32_e32 v10, 16, v8
	v_cmp_lt_i32_e32 vcc, v10, v9
	v_lshl_add_u64 v[6:7], v[42:43], 0, v[38:39]
	s_mov_b64 s[2:3], 0x8100000
	v_cndmask_b32_e32 v10, v8, v10, vcc
	v_lshlrev_b32_e32 v58, 2, v10
	v_xor_b32_e32 v10, 32, v8
	v_cmp_lt_i32_e32 vcc, v10, v9
	v_lshlrev_b32_e32 v1, 2, v1
	v_lshl_add_u64 v[42:43], v[6:7], 0, s[2:3]
	v_cndmask_b32_e32 v8, v8, v10, vcc
	v_lshlrev_b32_e32 v59, 2, v8
	s_mov_b64 s[2:3], 0
	s_mov_b32 s14, 0xfe03f81
	s_movk_i32 s15, 0xbf80
	s_movk_i32 s16, 0x80
	s_movk_i32 s17, 0x6f
	v_mov_b32_e32 v60, 0x358637bd
	s_mov_b32 s18, 0x800000
	s_mov_b32 s19, 0x80ff
	global_load_dwordx4 v[80:83], v[44:45], off
	global_load_dwordx4 v[84:87], v[44:45], off offset:1024
	global_load_dwordx4 v[88:91], v[44:45], off offset:2048
	global_load_dwordx4 v[92:95], v[44:45], off offset:3072
	s_waitcnt vmcnt(0)
	s_branch .LBB0_61

.LBB0_65:
	s_andn2_saveexec_b64 s[4:5], s[4:5]
	v_ashrrev_i32_e32 v23, 31, v22
	v_add_u32_e32 v38, 0xffffff80, v24
	v_lshlrev_b64 v[22:23], 26, v[22:23]
	v_lshl_add_u64 v[22:23], v[2:3], 0, v[22:23]
	v_lshlrev_b64 v[24:25], 12, v[38:39]
	v_lshl_add_u64 v[50:51], v[22:23], 0, v[24:25]
	s_or_b64 exec, exec, s[4:5]
	v_cmp_ne_u64_e32 vcc, 0, v[50:51]
	v_lshlrev_b32_e32 v38, 2, v40
	v_mov_b32_e32 v22, 0
	v_mov_b32_e32 v23, 0
	v_mov_b32_e32 v24, 0
	v_mov_b32_e32 v25, 0
	v_mov_b32_e32 v26, 0
	v_mov_b32_e32 v27, 0
	v_mov_b32_e32 v28, 0
	v_mov_b32_e32 v29, 0
	v_mov_b32_e32 v30, 0
	v_mov_b32_e32 v31, 0
	v_mov_b32_e32 v32, 0
	v_mov_b32_e32 v33, 0
	v_mov_b32_e32 v34, 0
	v_mov_b32_e32 v35, 0
	v_mov_b32_e32 v36, 0
	v_mov_b32_e32 v37, 0
	s_and_saveexec_b64 s[4:5], vcc
	s_cbranch_execz .Lp0_r1n
	v_lshl_add_u64 v[96:97], v[50:51], 0, v[38:39]
	global_load_dwordx4 v[26:29], v[96:97], off
	global_load_dwordx4 v[22:25], v[96:97], off offset:1024
	global_load_dwordx4 v[34:37], v[96:97], off offset:2048
	global_load_dwordx4 v[30:33], v[96:97], off offset:3072
.Lp0_r1n:
	s_or_b64 exec, exec, s[4:5]
	v_ashrrev_i32_e32 v49, 31, v48
	v_lshlrev_b64 v[98:99], 12, v[48:49]
	v_lshl_add_u64 v[98:99], v[46:47], 0, v[98:99]
	v_add_u32_e32 v50, s13, v48
	v_cmp_gt_i32_e32 vcc, s12, v50
	s_and_saveexec_b64 s[6:7], vcc
	s_cbranch_execz .Lp0_r2n
	v_mul_hi_i32 v6, v50, s14
	v_lshrrev_b32_e32 v7, 31, v6
	v_ashrrev_i32_e32 v6, 10, v6
	v_add_u32_e32 v6, v6, v7
	v_mul_i32_i24_e32 v7, 0xffffbf80, v6
	v_add3_u32 v8, s13, v7, v48
	v_cmp_gt_i32_e64 s[4:5], s16, v8
	s_and_saveexec_b64 s[8:9], s[4:5]
	s_xor_b64 s[8:9], exec, s[8:9]
	s_cbranch_execz .LBB0_80
	v_cmp_lt_i32_e64 s[4:5], s17, v8
	v_mov_b64_e32 v[52:53], 0
	s_and_saveexec_b64 s[10:11], s[4:5]
	v_add_u32_e32 v6, 0xffffff90, v8
	v_mov_b32_e32 v7, v39
	v_lshlrev_b64 v[6:7], 12, v[6:7]
	v_lshl_add_u64 v[52:53], v[4:5], 0, v[6:7]
	s_or_b64 exec, exec, s[10:11]
.LBB0_80:
	s_andn2_saveexec_b64 s[4:5], s[8:9]
	v_ashrrev_i32_e32 v7, 31, v6
	v_add_u32_e32 v8, 0xffffff80, v8
	v_mov_b32_e32 v9, v39
	v_lshlrev_b64 v[6:7], 26, v[6:7]
	v_lshl_add_u64 v[6:7], v[2:3], 0, v[6:7]
	v_lshlrev_b64 v[8:9], 12, v[8:9]
	v_lshl_add_u64 v[52:53], v[6:7], 0, v[8:9]
	s_or_b64 exec, exec, s[4:5]
	v_cmp_ne_u64_e64 s[4:5], 0, v[52:53]
	v_mov_b32_e32 v6, 0
	v_mov_b32_e32 v7, 0
	v_mov_b32_e32 v8, 0
	v_mov_b32_e32 v9, 0
	v_mov_b32_e32 v10, 0
	v_mov_b32_e32 v11, 0
	v_mov_b32_e32 v12, 0
	v_mov_b32_e32 v13, 0
	v_mov_b32_e32 v14, 0
	v_mov_b32_e32 v15, 0
	v_mov_b32_e32 v16, 0
	v_mov_b32_e32 v17, 0
	v_mov_b32_e32 v18, 0
	v_mov_b32_e32 v19, 0
	v_mov_b32_e32 v20, 0
	v_mov_b32_e32 v21, 0
	s_and_saveexec_b64 s[8:9], s[4:5]
	s_cbranch_execz .Lp0_r2l
	v_lshl_add_u64 v[96:97], v[52:53], 0, v[38:39]
	global_load_dwordx4 v[10:13], v[96:97], off
	global_load_dwordx4 v[6:9], v[96:97], off offset:1024
	global_load_dwordx4 v[18:21], v[96:97], off offset:2048
	global_load_dwordx4 v[14:17], v[96:97], off offset:3072
.Lp0_r2l:
	s_or_b64 exec, exec, s[8:9]
	v_ashrrev_i32_e32 v51, 31, v50
	v_lshlrev_b64 v[54:55], 12, v[50:51]
	v_lshl_add_u64 v[54:55], v[46:47], 0, v[54:55]
	s_waitcnt vmcnt(0)
	global_store_dwordx4 v[98:99], v[26:29], off
	global_store_dwordx4 v[98:99], v[22:25], off offset:1024
	global_store_dwordx4 v[98:99], v[34:37], off offset:2048
	global_store_dwordx4 v[98:99], v[30:33], off offset:3072
	global_store_dwordx4 v[54:55], v[10:13], off
	global_store_dwordx4 v[54:55], v[6:9], off offset:1024
	global_store_dwordx4 v[54:55], v[18:21], off offset:2048
	global_store_dwordx4 v[54:55], v[14:17], off offset:3072
	s_branch .LBB0_91
.Lp0_r2n:
	s_or_b64 exec, exec, s[6:7]
	s_waitcnt vmcnt(0)
	global_store_dwordx4 v[98:99], v[26:29], off
	global_store_dwordx4 v[98:99], v[22:25], off offset:1024
	global_store_dwordx4 v[98:99], v[34:37], off offset:2048
	global_store_dwordx4 v[98:99], v[30:33], off offset:3072
.LBB0_91:
	s_or_b64 exec, exec, s[6:7]
	s_nop 1
	v_mov_b32_e32 v52, v80
	v_mov_b32_e32 v53, v81
	v_mov_b32_e32 v54, v82
	v_mov_b32_e32 v55, v83
	v_mov_b32_e32 v64, v27
	v_mov_b32_e32 v65, v23
	v_mov_b32_e32 v62, v26
	v_mov_b32_e32 v63, v22
	v_mov_b32_e32 v72, v35
	v_mov_b32_e32 v73, v31
	v_pk_mul_f32 v[64:65], v[64:65], v[64:65]
	v_mov_b32_e32 v66, v28
	v_mov_b32_e32 v67, v24
	v_mov_b32_e32 v70, v34
	v_mov_b32_e32 v71, v30
	v_pk_mul_f32 v[72:73], v[72:73], v[72:73]
	v_pk_fma_f32 v[62:63], v[62:63], v[62:63], v[64:65]
	v_mov_b32_e32 v68, v29
	v_mov_b32_e32 v69, v25
	v_mov_b32_e32 v74, v36
	v_mov_b32_e32 v75, v32
	v_pk_fma_f32 v[64:65], v[70:71], v[70:71], v[72:73]
	v_pk_fma_f32 v[62:63], v[66:67], v[66:67], v[62:63]
	v_mov_b32_e32 v76, v37
	v_mov_b32_e32 v77, v33
	v_pk_fma_f32 v[64:65], v[74:75], v[74:75], v[64:65]
	v_pk_fma_f32 v[62:63], v[68:69], v[68:69], v[62:63]
	v_pk_fma_f32 v[64:65], v[76:77], v[76:77], v[64:65]
	v_add_f32_e32 v38, v62, v63
	v_add_f32_e32 v38, v38, v64
	v_add_f32_e32 v38, v38, v65
	ds_bpermute_b32 v51, v1, v38
	v_lshlrev_b64 v[48:49], 11, v[48:49]
	v_lshl_add_u64 v[48:49], v[42:43], 0, v[48:49]
	s_waitcnt lgkmcnt(0)
	v_add_f32_e32 v38, v38, v51
	ds_bpermute_b32 v51, v41, v38
	s_waitcnt lgkmcnt(0)
	v_add_f32_e32 v38, v38, v51
	ds_bpermute_b32 v51, v56, v38
	s_waitcnt lgkmcnt(0)
	v_add_f32_e32 v38, v38, v51
	ds_bpermute_b32 v51, v57, v38
	s_waitcnt lgkmcnt(0)
	v_add_f32_e32 v38, v38, v51
	ds_bpermute_b32 v51, v58, v38
	s_waitcnt lgkmcnt(0)
	v_add_f32_e32 v38, v38, v51
	ds_bpermute_b32 v51, v59, v38
	s_waitcnt lgkmcnt(0)
	v_add_f32_e32 v38, v38, v51
	v_fmamk_f32 v38, v38, 0x3a800000, v60
	v_mul_f32_e32 v51, 0x4b800000, v38
	v_cmp_gt_f32_e64 s[4:5], s18, v38
	v_pk_mul_f32 v[28:29], v[28:29], v[54:55]
	v_cndmask_b32_e64 v38, v38, v51, s[4:5]
	v_rsq_f32_e32 v38, v38
	v_pk_mul_f32 v[26:27], v[26:27], v[52:53]
	v_mul_f32_e32 v51, 0x45800000, v38
	v_cndmask_b32_e64 v38, v38, v51, s[4:5]
	v_pk_mul_f32 v[28:29], v[28:29], v[38:39] op_sel_hi:[1,0]
	v_pk_mul_f32 v[26:27], v[26:27], v[38:39] op_sel_hi:[1,0]
	s_nop 0
	v_cvt_pk_bf16_f32 v26, v26, v27
	v_cvt_pk_bf16_f32 v27, v28, v29
	global_store_dwordx2 v[48:49], v[26:27], off
	s_nop 1
	v_mov_b32_e32 v26, v84
	v_mov_b32_e32 v27, v85
	v_mov_b32_e32 v28, v86
	v_mov_b32_e32 v29, v87
	v_pk_mul_f32 v[24:25], v[24:25], v[28:29]
	v_pk_mul_f32 v[22:23], v[22:23], v[26:27]
	v_pk_mul_f32 v[24:25], v[24:25], v[38:39] op_sel_hi:[1,0]
	v_pk_mul_f32 v[22:23], v[22:23], v[38:39] op_sel_hi:[1,0]
	s_nop 0
	v_cvt_pk_bf16_f32 v22, v22, v23
	v_cvt_pk_bf16_f32 v23, v24, v25
	global_store_dwordx2 v[48:49], v[22:23], off offset:512
	s_nop 1
	v_mov_b32_e32 v22, v88
	v_mov_b32_e32 v23, v89
	v_mov_b32_e32 v24, v90
	v_mov_b32_e32 v25, v91
	v_pk_mul_f32 v[24:25], v[36:37], v[24:25]
	v_pk_mul_f32 v[22:23], v[34:35], v[22:23]
	v_pk_mul_f32 v[24:25], v[24:25], v[38:39] op_sel_hi:[1,0]
	v_pk_mul_f32 v[22:23], v[22:23], v[38:39] op_sel_hi:[1,0]
	s_nop 0
	v_cvt_pk_bf16_f32 v22, v22, v23
	v_cvt_pk_bf16_f32 v23, v24, v25
	global_store_dwordx2 v[48:49], v[22:23], off offset:1024
	s_nop 1
	v_mov_b32_e32 v22, v92
	v_mov_b32_e32 v23, v93
	v_mov_b32_e32 v24, v94
	v_mov_b32_e32 v25, v95
	v_pk_mul_f32 v[24:25], v[32:33], v[24:25]
	v_pk_mul_f32 v[22:23], v[30:31], v[22:23]
	v_pk_mul_f32 v[24:25], v[24:25], v[38:39] op_sel_hi:[1,0]
	v_pk_mul_f32 v[22:23], v[22:23], v[38:39] op_sel_hi:[1,0]
	s_nop 0
	v_cvt_pk_bf16_f32 v22, v22, v23
	v_cvt_pk_bf16_f32 v23, v24, v25
	global_store_dwordx2 v[48:49], v[22:23], off offset:1536
	s_and_saveexec_b64 s[4:5], vcc
	s_cbranch_execz .LBB0_60
	s_nop 1
	v_mov_b32_e32 v22, v80
	v_mov_b32_e32 v23, v81
	v_mov_b32_e32 v24, v82
	v_mov_b32_e32 v25, v83
	v_mov_b32_e32 v28, v7
	v_mov_b32_e32 v29, v11
	v_mov_b32_e32 v26, v6
	v_mov_b32_e32 v27, v10
	v_mov_b32_e32 v36, v15
	v_mov_b32_e32 v37, v19
	v_pk_mul_f32 v[28:29], v[28:29], v[28:29]
	v_mov_b32_e32 v30, v8
	v_mov_b32_e32 v31, v12
	v_mov_b32_e32 v34, v14
	v_mov_b32_e32 v35, v18
	v_pk_mul_f32 v[36:37], v[36:37], v[36:37]
	v_pk_fma_f32 v[26:27], v[26:27], v[26:27], v[28:29]
	v_mov_b32_e32 v32, v9
	v_mov_b32_e32 v33, v13
	v_mov_b32_e32 v48, v16
	v_mov_b32_e32 v49, v20
	v_pk_fma_f32 v[28:29], v[34:35], v[34:35], v[36:37]
	v_pk_fma_f32 v[26:27], v[30:31], v[30:31], v[26:27]
	v_mov_b32_e32 v52, v17
	v_mov_b32_e32 v53, v21
	v_pk_fma_f32 v[28:29], v[48:49], v[48:49], v[28:29]
	v_pk_fma_f32 v[26:27], v[32:33], v[32:33], v[26:27]
	v_pk_fma_f32 v[28:29], v[52:53], v[52:53], v[28:29]
	v_add_f32_e32 v26, v26, v27
	v_add_f32_e32 v26, v29, v26
	v_add_f32_e32 v26, v28, v26
	ds_bpermute_b32 v27, v1, v26
	v_ashrrev_i32_e32 v51, 31, v50
	s_waitcnt lgkmcnt(0)
	v_add_f32_e32 v26, v26, v27
	ds_bpermute_b32 v27, v41, v26
	s_waitcnt lgkmcnt(0)
	v_add_f32_e32 v26, v26, v27
	ds_bpermute_b32 v27, v56, v26
	s_waitcnt lgkmcnt(0)
	v_add_f32_e32 v26, v26, v27
	ds_bpermute_b32 v27, v57, v26
	s_waitcnt lgkmcnt(0)
	v_add_f32_e32 v26, v26, v27
	ds_bpermute_b32 v27, v58, v26
	s_waitcnt lgkmcnt(0)
	v_add_f32_e32 v26, v26, v27
	ds_bpermute_b32 v27, v59, v26
	s_waitcnt lgkmcnt(0)
	v_add_f32_e32 v26, v26, v27
	v_fmamk_f32 v26, v26, 0x3a800000, v60
	v_mul_f32_e32 v27, 0x4b800000, v26
	v_cmp_gt_f32_e32 vcc, s18, v26
	v_pk_mul_f32 v[24:25], v[12:13], v[24:25]
	v_cndmask_b32_e32 v26, v26, v27, vcc
	v_rsq_f32_e32 v28, v26
	v_pk_mul_f32 v[22:23], v[10:11], v[22:23]
	v_lshlrev_b64 v[26:27], 11, v[50:51]
	v_lshl_add_u64 v[26:27], v[42:43], 0, v[26:27]
	v_mul_f32_e32 v29, 0x45800000, v28
	v_cndmask_b32_e32 v28, v28, v29, vcc
	v_pk_mul_f32 v[24:25], v[24:25], v[28:29] op_sel_hi:[1,0]
	v_pk_mul_f32 v[22:23], v[22:23], v[28:29] op_sel_hi:[1,0]
	s_nop 0
	v_cvt_pk_bf16_f32 v22, v22, v23
	v_cvt_pk_bf16_f32 v23, v24, v25
	global_store_dwordx2 v[26:27], v[22:23], off
	s_nop 1
	v_mov_b32_e32 v22, v84
	v_mov_b32_e32 v23, v85
	v_mov_b32_e32 v24, v86
	v_mov_b32_e32 v25, v87
	v_pk_mul_f32 v[24:25], v[8:9], v[24:25]
	v_pk_mul_f32 v[22:23], v[6:7], v[22:23]
	v_pk_mul_f32 v[24:25], v[24:25], v[28:29] op_sel_hi:[1,0]
	v_pk_mul_f32 v[22:23], v[22:23], v[28:29] op_sel_hi:[1,0]
	s_nop 0
	v_cvt_pk_bf16_f32 v22, v22, v23
	v_cvt_pk_bf16_f32 v23, v24, v25
	global_store_dwordx2 v[26:27], v[22:23], off offset:512
	s_nop 1
	v_mov_b32_e32 v22, v88
	v_mov_b32_e32 v23, v89
	v_mov_b32_e32 v24, v90
	v_mov_b32_e32 v25, v91
	v_pk_mul_f32 v[24:25], v[20:21], v[24:25]
	v_pk_mul_f32 v[22:23], v[18:19], v[22:23]
	v_pk_mul_f32 v[24:25], v[24:25], v[28:29] op_sel_hi:[1,0]
	v_pk_mul_f32 v[22:23], v[22:23], v[28:29] op_sel_hi:[1,0]
	s_nop 0
	v_cvt_pk_bf16_f32 v22, v22, v23
	v_cvt_pk_bf16_f32 v23, v24, v25
	global_store_dwordx2 v[26:27], v[22:23], off offset:1024
	s_nop 1
	v_mov_b32_e32 v22, v92
	v_mov_b32_e32 v23, v93
	v_mov_b32_e32 v24, v94
	v_mov_b32_e32 v25, v95
	v_pk_mul_f32 v[24:25], v[16:17], v[24:25]
	v_pk_mul_f32 v[22:23], v[14:15], v[22:23]
	v_pk_mul_f32 v[24:25], v[24:25], v[28:29] op_sel_hi:[1,0]
	v_pk_mul_f32 v[22:23], v[22:23], v[28:29] op_sel_hi:[1,0]
	s_nop 0
	v_cvt_pk_bf16_f32 v22, v22, v23
	v_cvt_pk_bf16_f32 v23, v24, v25
	global_store_dwordx2 v[26:27], v[22:23], off offset:1536
	s_branch .LBB0_60
